# v105 + non-temporal loads for the diff-attention Q fragments (read once per unit)
# baseline (speedup 1.0000x reference)
; #define LAS __attribute__((address_space(3)))
; __device__ __forceinline__ void diff_unit(const Params& p, LAS unsigned char* lds, int b, int h, int qb, float lam) {
;     ...
;     const int tid = tid_, lane = tid & 63, wid = __builtin_amdgcn_readfirstlane(tid >> 6), c = lane & 31, hh = lane >> 5;
;     const bf16_t* QK = (const bf16_t*)(p.ws + WS_QK); const bf16_t* VT = (const bf16_t*)(p.ws + WS_VT); bf16_t* AO = (bf16_t*)(p.ws + WS_AO);
;     const size_t rowbase = (size_t)b * SEQ;
;     const int q0 = qb * 256 + wid * 32, mylast = q0 >> 6, NT = 4 * qb + 4;
;     const int xk = ((c >> 1) & 7) ^ hh, xv = ((c >> 1) & 7) ^ (2 * hh);
;     LAS float* tab = (LAS float*)(lds + A_TAB);
;     if (tid < 256) { const int d = tid - 64, n = d < 0 ? -d : d; int bk = (n < 8) ? n : min(15, 2 + (31 - __clz(n * n))); if (d < 0) bk += 16;
;         tab[tid] = (p.rel_bias[bk * 8 + h] - p.rel_bias[15 * 8 + h]) * LOG2E; }
;     const bf16_t* Vg0 = VT + ((size_t)h * 512 + (size_t)b * 64) * 8192;
;     unsigned* park = (unsigned*)(p.ws + WS_PARK) + ((size_t)(blockIdx.x * 8 + wid) * 32) * 64 + lane;
;     const bf16x8 ones = (bf16x8){0x3f80, 0x3f80, 0x3f80, 0x3f80, 0x3f80, 0x3f80, 0x3f80, 0x3f80};
;     f32x16 O[4];
; #pragma unroll
;     for (int mp = 0; mp < 2; ++mp) {
;         const bf16_t* Kg0 = (const bf16_t*)(p.ws + WS_KD) + ((size_t)(2 * h + mp) * MT + rowbase) * 64;
;         tile_dma<64>(Kg0, Vg0, lds + A_KOFF, lds + A_VOFF, wid, lane);
;         const bf16_t* qp = QK + (rowbase + q0 + c) * 4096 + h * 128 + 64 * mp + hh * 8;
;         bf16x8 qf[4];
; #pragma unroll
;         for (int ks = 0; ks < 4; ++ks) qf[ks] = *(const bf16x8*)(qp + 16 * ks);
; #pragma unroll
;         for (int db = 0; db < 4; ++db) O[db] = (f32x16){};
;         f32x16 L = (f32x16){};
;         f32x16 negm = (f32x16){};
;         float m = 0.f;
;         asm volatile("s_waitcnt vmcnt(0)" ::: "memory");
;         __syncthreads();
;         for (int jt = 0; jt < NT; ++jt) {
;             const int cur = jt & 1;
;             if (jt + 1 < NT) tile_dma<64>(Kg0 + (size_t)(jt + 1) * 4096, Vg0 + (size_t)(jt + 1) * 8192, lds + A_KOFF + (cur ^ 1) * A_KBUF, lds + A_VOFF + (cur ^ 1) * A_VBUF, wid, lane);
;             if (jt <= mylast) {
.LBB0_276:
	s_or_b64 exec, exec, s[10:11]
	s_ashr_i32 s88, s1, 6
	s_lshl_b32 s1, s66, 8
	s_lshl_b32 s4, s88, 5
	s_bfe_u32 s3, s72, 0x30005
	s_add_i32 s77, s4, s1
	s_lshl_b32 s86, s3, 12
	s_ashr_i32 s76, s77, 6
	s_lshl_b32 s1, s3, 20
	s_add_u32 s1, s14, s1
	s_addc_u32 s3, s15, 0
	s_lshl_b32 s4, s0, 23
	s_add_u32 s4, s1, s4
	s_addc_u32 s5, s3, 0
	s_lshl_b32 s1, s88, 3
	v_bfe_u32 v117, v2, 3, 3
	v_and_b32_e32 v164, 63, v2
	v_lshrrev_b32_e32 v3, 1, v2
	v_or_b32_e32 v0, s1, v117
	s_and_b32 s1, s1, 32
	v_and_b32_e32 v114, 16, v3
	s_lshl_b32 s6, s88, 2
	v_bfe_u32 v115, v164, 3, 2
	v_lshrrev_b32_e32 v0, 1, v0
	s_and_b32 s22, s6, 4
	v_or3_b32 v4, v115, v114, s1
	v_xor_b32_e32 v116, v0, v2
	s_and_b32 s3, s6, 8
	v_or_b32_e32 v4, s22, v4
	v_lshlrev_b32_e32 v0, 3, v116
	s_lshl_b32 s23, s88, 4
	v_or_b32_e32 v120, s3, v4
	v_and_b32_e32 v12, 56, v0
	v_or_b32_e32 v4, s23, v117
	v_bfe_u32 v0, v2, 4, 2
	s_lshl_b32 s6, s88, 10
	v_ashrrev_i32_e32 v5, 31, v4
	v_bitop3_b32 v118, v0, v2, 63 bitop3:0x78
	s_add_i32 s78, s6, 0
	s_lshl_b32 s9, s88, 1
	v_lshlrev_b64 v[4:5], 7, v[4:5]
	v_lshlrev_b32_e32 v0, 4, v118
	v_lshl_add_u64 v[6:7], s[4:5], 0, v[4:5]
	v_and_b32_e32 v0, 0x70, v0
	s_add_i32 s84, s78, s6
	s_or_b32 s6, s9, 1
	v_lshl_add_u64 v[170:171], v[6:7], 0, v[0:1]
	v_lshl_or_b32 v6, s6, 3, v117
	v_ashrrev_i32_e32 v7, 31, v6
	s_lshl_b32 s79, s6, 10
	v_lshlrev_b64 v[8:9], 7, v[6:7]
	v_lshrrev_b32_e32 v6, 1, v6
	s_add_i32 s85, s79, 0
	s_lshl_b32 s87, s0, 16
	s_add_i32 s81, s84, 0x8000
	v_xor_b32_e32 v119, v6, v2
	s_add_i32 s82, s85, 0x8000
	s_ashr_i32 s6, s77, 31
	v_lshlrev_b32_e32 v6, 4, v119
	s_add_u32 s73, s86, s77
	v_and_b32_e32 v196, 31, v2
	v_lshl_add_u64 v[10:11], s[4:5], 0, v[8:9]
	v_and_b32_e32 v6, 0x70, v6
	v_mov_b32_e32 v7, v1
	s_addc_u32 s74, 0, s6
	v_lshl_add_u64 v[172:173], v[10:11], 0, v[6:7]
	v_or_b32_e32 v10, s73, v196
	v_mov_b32_e32 v11, s74
	v_lshlrev_b64 v[10:11], 13, v[10:11]
	v_lshl_add_u64 v[10:11], s[18:19], 0, v[10:11]
	s_lshl_b32 s6, s0, 8
	v_lshl_add_u64 v[10:11], v[10:11], 0, s[6:7]
	s_or_b32 s6, s86, s87
	v_bfe_u32 v195, v2, 5, 1
	s_lshl_b32 s6, s6, 7
	v_lshlrev_b32_e32 v112, 4, v195
	v_mov_b32_e32 v113, v1
	s_add_u32 s10, s27, s6
	v_lshl_add_u64 v[174:175], v[10:11], 0, v[112:113]
	s_addc_u32 s11, s35, 0
	v_lshlrev_b32_e32 v10, 7, v120
	v_mov_b32_e32 v11, v1
	v_lshl_add_u64 v[10:11], s[10:11], 0, v[10:11]
	v_lshlrev_b32_e32 v182, 1, v12
	v_mov_b32_e32 v183, v1
	v_lshl_add_u64 v[10:11], v[10:11], 0, v[182:183]
	s_mov_b32 m0, s78
	s_add_u32 s4, s4, 0x4000
	global_load_lds_dwordx4 v[10:11], off
	s_mov_b32 m0, s81
	s_addc_u32 s5, s5, 0
	global_load_lds_dwordx4 v[170:171], off
	s_mov_b32 m0, s82
	s_add_i32 s83, s78, 0x4000
	global_load_lds_dwordx4 v[172:173], off
	global_load_dwordx4 v[156:159], v[174:175], off nt
	global_load_dwordx4 v[152:155], v[174:175], off offset:32 nt
	global_load_dwordx4 v[148:151], v[174:175], off offset:64 nt
	global_load_dwordx4 v[144:147], v[174:175], off offset:96 nt
	v_lshl_add_u64 v[10:11], v[10:11], 0, s[42:43]
	s_mov_b32 m0, s83
	v_lshl_add_u64 v[4:5], s[4:5], 0, v[4:5]
	s_add_i32 s84, s84, 0xc000
	s_waitcnt vmcnt(0)
	s_waitcnt vmcnt(0) lgkmcnt(0)
	s_barrier
	global_load_lds_dwordx4 v[10:11], off
	v_lshl_add_u64 v[176:177], v[4:5], 0, v[0:1]
	s_mov_b32 m0, s84
	v_lshl_add_u64 v[4:5], s[4:5], 0, v[8:9]
	s_add_i32 s85, s85, 0xc000
	global_load_lds_dwordx4 v[176:177], off
	v_lshl_add_u64 v[178:179], v[4:5], 0, v[6:7]
	s_mov_b32 m0, s85
	v_bfe_u32 v0, v2, 1, 3
	global_load_lds_dwordx4 v[178:179], off
	v_bitop3_b32 v2, v3, v195, 7 bitop3:0x6c
	s_cmp_gt_i32 s76, -1
	v_lshl_add_u32 v197, v196, 7, 0
	v_lshlrev_b32_e32 v203, 4, v2
	v_or_b32_e32 v2, s77, v196
	s_cselect_b64 s[64:65], -1, 0
	v_sub_u32_e32 v202, v2, v112
	s_mov_b64 s[4:5], -1
	s_and_b64 vcc, exec, s[64:65]
	v_add_u32_e32 v204, v197, v203
	v_xor_b32_e32 v113, 32, v203
	v_xor_b32_e32 v121, 64, v203
	v_xor_b32_e32 v122, 0x60, v203
	s_cbranch_vccz .LBB0_280
; #define LAS __attribute__((address_space(3)))
; #define MFMA32(a, b, c) __builtin_amdgcn_mfma_f32_32x32x16_bf16((a), (b), (c), 0, 0, 0)
; #define SCHEDB() __builtin_amdgcn_sched_barrier(0)
; __device__ __forceinline__ void diff_unit(const Params& p, LAS unsigned char* lds, int b, int h, int qb, float lam) {
;     ...
;                 {
;                     bf16x8 a[2][2];
;                     { const int co = (0 ^ xk) << 4; a[0][0] = *(const LAS bf16x8*)(kb + co); a[0][1] = *(const LAS bf16x8*)(kb + 4096 + co); }
; #pragma unroll
;                     for (int ks = 0; ks < 4; ++ks) {
;                         if (ks + 1 < 4) { const int co = ((2 * (ks + 1)) ^ xk) << 4; a[(ks + 1) & 1][0] = *(const LAS bf16x8*)(kb + co); a[(ks + 1) & 1][1] = *(const LAS bf16x8*)(kb + 4096 + co); }
;                         if (ks == 0) { s0 = MFMA32(a[0][0], qf[0], negm); s1 = MFMA32(a[0][1], qf[0], negm); }
;                         else { s0 = MFMA32(a[ks & 1][0], qf[ks], s0); s1 = MFMA32(a[ks & 1][1], qf[ks], s1); }
;                         SCHEDB();
;                     }
;                 }
;                 if ((q0 - (64 * jt + 63)) < 91) {
;                     const int idx0 = (q0 + c) - (64 * jt + 16 * hh) + 64;
; #pragma unroll
;                     for (int r = 0; r < 16; ++r) { s0[r] += tab[min(idx0 - r, 255)]; s1[r] += tab[min(idx0 - 32 - r, 255)]; if ((r & 3) == 3) SCHEDB(); }
;                 }
	ds_read_b128 v[2:5], v204
	ds_read_b128 v[18:21], v204 offset:4096
	v_xor_b32_e32 v205, 32, v203
	v_add_u32_e32 v22, v197, v205
	ds_read_b128 v[34:37], v22
	ds_read_b128 v[38:41], v22 offset:4096
	s_waitcnt lgkmcnt(0)
	v_mfma_f32_32x32x16_bf16 v[2:17], v[2:5], v[156:159], 0
	v_mfma_f32_32x32x16_bf16 v[18:33], v[18:21], v[156:159], 0
	v_mfma_f32_32x32x16_bf16 v[2:17], v[34:37], v[152:155], v[2:17]
	v_xor_b32_e32 v206, 64, v203
	v_add_u32_e32 v42, v197, v206
	ds_read_b128 v[34:37], v42
	ds_read_b128 v[42:45], v42 offset:4096
	v_mfma_f32_32x32x16_bf16 v[18:33], v[38:41], v[152:155], v[18:33]
	s_waitcnt lgkmcnt(0)
	v_mfma_f32_32x32x16_bf16 v[2:17], v[34:37], v[148:151], v[2:17]
	v_xor_b32_e32 v207, 0x60, v203
	v_add_u32_e32 v38, v197, v207
	ds_read_b128 v[34:37], v38
	ds_read_b128 v[38:41], v38 offset:4096
	v_mfma_f32_32x32x16_bf16 v[18:33], v[42:45], v[148:151], v[18:33]
	s_waitcnt lgkmcnt(0)
	v_mfma_f32_32x32x16_bf16 v[2:17], v[34:37], v[144:147], v[2:17]
	v_mfma_f32_32x32x16_bf16 v[18:33], v[38:41], v[144:147], v[18:33]
	s_cmpk_gt_u32 s77, 0x99
	s_cbranch_scc1 .LBB0_279
	s_add_i32 s4, 0, 0x10000
	v_min_i32_e32 v36, 0xc0, v202
	v_lshl_add_u32 v37, v36, 2, s4
	v_min_i32_e32 v36, 0xe0, v202
	v_lshl_add_u32 v38, v36, 2, s4
	v_min_i32_e32 v36, 0xc1, v202
	v_lshl_add_u32 v39, v36, 2, s4
	v_min_i32_e32 v36, 0xe1, v202
	v_min_i32_e32 v34, 0xbf, v202
	v_min_i32_e32 v35, 0xdf, v202
	v_lshl_add_u32 v40, v36, 2, s4
	v_min_i32_e32 v36, 0xc2, v202
	v_lshl_add_u32 v34, v34, 2, s4
	v_lshl_add_u32 v35, v35, 2, s4
	v_lshl_add_u32 v41, v36, 2, s4
	v_min_i32_e32 v36, 0xe2, v202
	v_lshl_add_u32 v42, v36, 2, s4
	ds_read_b32 v34, v34 offset:256
	ds_read_b32 v36, v35 offset:128
	ds_read_b32 v35, v37 offset:252
	ds_read_b32 v37, v38 offset:124
	ds_read_b32 v38, v39 offset:248
	ds_read_b32 v40, v40 offset:120
	ds_read_b32 v39, v41 offset:244
	ds_read_b32 v41, v42 offset:116
	v_min_i32_e32 v44, 0xc4, v202
	v_lshl_add_u32 v45, v44, 2, s4
	v_min_i32_e32 v44, 0xe4, v202
	v_lshl_add_u32 v46, v44, 2, s4
	v_min_i32_e32 v44, 0xc5, v202
	v_lshl_add_u32 v47, v44, 2, s4
	v_min_i32_e32 v44, 0xe5, v202
	v_min_i32_e32 v42, 0xc3, v202
	v_min_i32_e32 v43, 0xe3, v202
	v_lshl_add_u32 v48, v44, 2, s4
	v_min_i32_e32 v44, 0xc6, v202
	v_lshl_add_u32 v42, v42, 2, s4
	v_lshl_add_u32 v43, v43, 2, s4
	v_lshl_add_u32 v49, v44, 2, s4
	v_min_i32_e32 v44, 0xe6, v202
	v_lshl_add_u32 v50, v44, 2, s4
	ds_read_b32 v42, v42 offset:240
	ds_read_b32 v44, v43 offset:112
	ds_read_b32 v43, v45 offset:236
	ds_read_b32 v45, v46 offset:108
	ds_read_b32 v46, v47 offset:232
	ds_read_b32 v48, v48 offset:104
	ds_read_b32 v47, v49 offset:228
	ds_read_b32 v49, v50 offset:100
	v_min_i32_e32 v52, 0xc8, v202
	v_lshl_add_u32 v53, v52, 2, s4
	v_min_i32_e32 v52, 0xe8, v202
	v_lshl_add_u32 v54, v52, 2, s4
	v_min_i32_e32 v52, 0xc9, v202
	v_lshl_add_u32 v55, v52, 2, s4
	v_min_i32_e32 v52, 0xe9, v202
	v_min_i32_e32 v50, 0xc7, v202
	v_min_i32_e32 v51, 0xe7, v202
	v_lshl_add_u32 v56, v52, 2, s4
	v_min_i32_e32 v52, 0xca, v202
	v_lshl_add_u32 v50, v50, 2, s4
	v_lshl_add_u32 v51, v51, 2, s4
	v_lshl_add_u32 v57, v52, 2, s4
	v_min_i32_e32 v52, 0xea, v202
	v_lshl_add_u32 v58, v52, 2, s4
	ds_read_b32 v50, v50 offset:224
	ds_read_b32 v52, v51 offset:96
	ds_read_b32 v51, v53 offset:220
	ds_read_b32 v53, v54 offset:92
	ds_read_b32 v54, v55 offset:216
	ds_read_b32 v56, v56 offset:88
	ds_read_b32 v55, v57 offset:212
	ds_read_b32 v57, v58 offset:84
	v_min_i32_e32 v58, 0xcb, v202
	s_waitcnt lgkmcnt(0)
	v_pk_add_f32 v[2:3], v[2:3], v[34:35]
	v_min_i32_e32 v34, 0xee, v202
	v_lshl_add_u32 v58, v58, 2, s4
	v_min_i32_e32 v59, 0xeb, v202
	v_min_i32_e32 v60, 0xcc, v202
	v_min_i32_e32 v61, 0xec, v202
	v_min_i32_e32 v62, 0xcd, v202
	v_min_i32_e32 v63, 0xed, v202
	v_min_i32_e32 v64, 0xce, v202
	v_pk_add_f32 v[4:5], v[4:5], v[38:39]
	v_lshl_add_u32 v39, v34, 2, s4
	v_lshl_add_u32 v59, v59, 2, s4
	v_lshl_add_u32 v60, v60, 2, s4
	v_lshl_add_u32 v61, v61, 2, s4
	v_lshl_add_u32 v62, v62, 2, s4
	v_lshl_add_u32 v63, v63, 2, s4
	v_lshl_add_u32 v64, v64, 2, s4
	v_pk_add_f32 v[8:9], v[8:9], v[46:47]
	v_pk_add_f32 v[6:7], v[6:7], v[42:43]
	ds_read_b32 v34, v58 offset:208
	ds_read_b32 v38, v59 offset:80
	ds_read_b32 v42, v62 offset:200
	ds_read_b32 v43, v64 offset:196
	ds_read_b32 v35, v60 offset:204
	ds_read_b32 v47, v39 offset:68
	ds_read_b32 v46, v63 offset:72
	ds_read_b32 v39, v61 offset:76
	v_pk_add_f32 v[12:13], v[12:13], v[54:55]
	v_pk_add_f32 v[10:11], v[10:11], v[50:51]
	s_waitcnt lgkmcnt(0)
	v_pk_add_f32 v[16:17], v[16:17], v[42:43]
	v_pk_add_f32 v[14:15], v[14:15], v[34:35]
	v_pk_add_f32 v[20:21], v[20:21], v[40:41]
	v_pk_add_f32 v[18:19], v[18:19], v[36:37]
	v_pk_add_f32 v[24:25], v[24:25], v[48:49]
	v_pk_add_f32 v[22:23], v[22:23], v[44:45]
	v_pk_add_f32 v[28:29], v[28:29], v[56:57]
	v_pk_add_f32 v[26:27], v[26:27], v[52:53]
	v_pk_add_f32 v[32:33], v[32:33], v[46:47]
	v_pk_add_f32 v[30:31], v[30:31], v[38:39]

; __device__ __forceinline__ unsigned cvtpk(float lo, float hi) { f32x2_t v = {lo, hi}; bf16x2_t b = __builtin_convertvector(v, bf16x2_t); return __builtin_bit_cast(unsigned, b); }
; __device__ __forceinline__ void diff_unit(const Params& p, LAS unsigned char* lds, int b, int h, int qb, float lam) {
;     ...
;             asm volatile("s_waitcnt vmcnt(0)" ::: "memory");
;             __syncthreads();
;         }
; #pragma unroll
;         for (int r = 0; r < 16; ++r) { const float a = (mp == 0 ? 1.0f : lam) / L[r];
; #pragma unroll
;             for (int db = 0; db < 4; ++db) O[db][r] *= a; }
;         if (mp == 0) {
; #pragma unroll
;             for (int db = 0; db < 4; ++db)
; #pragma unroll
;                 for (int j = 0; j < 8; ++j) park[(db * 8 + j) * 64] = cvtpk(O[db][2 * j], O[db][2 * j + 1]);
.LBB0_296:
	v_readlane_b32 s0, v245, 1
	s_add_i32 s6, s88, s0
	s_lshl_b64 s[0:1], s[6:7], 13
	s_add_u32 s10, s17, s0
	s_addc_u32 s11, s26, s1
	v_lshlrev_b32_e32 v2, 2, v164
	v_mov_b32_e32 v3, v1
	v_lshl_add_u64 v[164:165], s[10:11], 0, v[2:3]
	s_nop 3
	v_div_scale_f32 v3, s[0:1], v81, v81, 1.0
	v_rcp_f32_e32 v4, v3
	s_waitcnt vmcnt(0)
	s_barrier
	v_fma_f32 v5, -v3, v4, 1.0
	v_fmac_f32_e32 v4, v5, v4
	v_div_scale_f32 v5, vcc, 1.0, v81, 1.0
	v_mul_f32_e32 v6, v5, v4
	v_fma_f32 v7, -v3, v6, v5
	v_fmac_f32_e32 v6, v7, v4
	v_fma_f32 v3, -v3, v6, v5
	v_div_fmas_f32 v3, v3, v4, v6
	v_div_fixup_f32 v5, v3, v81, 1.0
	v_div_scale_f32 v3, s[0:1], v80, v80, 1.0
	v_rcp_f32_e32 v4, v3
	v_mov_b32_e32 v183, v1
	s_mov_b32 m0, s78
	v_fma_f32 v6, -v3, v4, 1.0
	v_fmac_f32_e32 v4, v6, v4
	v_div_scale_f32 v6, vcc, 1.0, v80, 1.0
	v_mul_f32_e32 v7, v6, v4
	v_fma_f32 v8, -v3, v7, v6
	v_fmac_f32_e32 v7, v8, v4
	v_fma_f32 v3, -v3, v7, v6
	v_div_fmas_f32 v3, v3, v4, v7
	v_div_fixup_f32 v4, v3, v80, 1.0
	v_div_scale_f32 v3, s[0:1], v83, v83, 1.0
	v_rcp_f32_e32 v12, v3
	v_pk_mul_f32 v[6:7], v[64:65], v[4:5]
	v_pk_mul_f32 v[8:9], v[48:49], v[4:5]
	v_pk_mul_f32 v[10:11], v[32:33], v[4:5]
	v_fma_f32 v13, -v3, v12, 1.0
	v_fmac_f32_e32 v12, v13, v12
	v_div_scale_f32 v13, vcc, 1.0, v83, 1.0
	v_mul_f32_e32 v14, v13, v12
	v_fma_f32 v15, -v3, v14, v13
	v_fmac_f32_e32 v14, v15, v12
	v_fma_f32 v3, -v3, v14, v13
	v_div_fmas_f32 v3, v3, v12, v14
	v_div_fixup_f32 v13, v3, v83, 1.0
	v_div_scale_f32 v3, s[0:1], v82, v82, 1.0
	v_rcp_f32_e32 v12, v3
	v_pk_mul_f32 v[4:5], v[16:17], v[4:5]
	v_add_u32_e32 v211, v197, v205
	v_add_u32_e32 v210, v197, v206
	v_fma_f32 v14, -v3, v12, 1.0
	v_fmac_f32_e32 v12, v14, v12
	v_div_scale_f32 v14, vcc, 1.0, v82, 1.0
	v_mul_f32_e32 v15, v14, v12
	v_fma_f32 v16, -v3, v15, v14
	v_fmac_f32_e32 v15, v16, v12
	v_fma_f32 v3, -v3, v15, v14
	v_div_fmas_f32 v3, v3, v12, v15
	v_div_fixup_f32 v12, v3, v82, 1.0
	v_div_scale_f32 v3, s[0:1], v85, v85, 1.0
	v_pk_mul_f32 v[14:15], v[66:67], v[12:13]
	v_pk_mul_f32 v[16:17], v[50:51], v[12:13]
	v_pk_mul_f32 v[32:33], v[34:35], v[12:13]
	v_pk_mul_f32 v[12:13], v[18:19], v[12:13]
	v_rcp_f32_e32 v18, v3
	v_add_u32_e32 v209, v197, v207
	v_fma_f32 v19, -v3, v18, 1.0
	v_fmac_f32_e32 v18, v19, v18
	v_div_scale_f32 v19, vcc, 1.0, v85, 1.0
	v_mul_f32_e32 v34, v19, v18
	v_fma_f32 v35, -v3, v34, v19
	v_fmac_f32_e32 v34, v35, v18
	v_fma_f32 v3, -v3, v34, v19
	v_div_fmas_f32 v3, v3, v18, v34
	v_div_fixup_f32 v19, v3, v85, 1.0
	v_div_scale_f32 v3, s[0:1], v84, v84, 1.0
	v_rcp_f32_e32 v18, v3
	s_nop 0
	v_fma_f32 v34, -v3, v18, 1.0
	v_fmac_f32_e32 v18, v34, v18
	v_div_scale_f32 v34, vcc, 1.0, v84, 1.0
	v_mul_f32_e32 v35, v34, v18
	v_fma_f32 v48, -v3, v35, v34
	v_fmac_f32_e32 v35, v48, v18
	v_fma_f32 v3, -v3, v35, v34
	v_div_fmas_f32 v3, v3, v18, v35
	v_div_fixup_f32 v18, v3, v84, 1.0
	v_div_scale_f32 v3, s[0:1], v87, v87, 1.0
	v_pk_mul_f32 v[34:35], v[68:69], v[18:19]
	v_pk_mul_f32 v[48:49], v[52:53], v[18:19]
	v_pk_mul_f32 v[36:37], v[36:37], v[18:19]
	v_pk_mul_f32 v[18:19], v[20:21], v[18:19]
	v_rcp_f32_e32 v20, v3
	s_nop 0
	v_fma_f32 v21, -v3, v20, 1.0
	v_fmac_f32_e32 v20, v21, v20
	v_div_scale_f32 v21, vcc, 1.0, v87, 1.0
	v_mul_f32_e32 v50, v21, v20
	v_fma_f32 v51, -v3, v50, v21
	v_fmac_f32_e32 v50, v51, v20
	v_fma_f32 v3, -v3, v50, v21
	v_div_fmas_f32 v3, v3, v20, v50
	v_div_fixup_f32 v21, v3, v87, 1.0
	v_div_scale_f32 v3, s[0:1], v86, v86, 1.0
	v_rcp_f32_e32 v20, v3
	s_nop 0
	v_fma_f32 v50, -v3, v20, 1.0
	v_fmac_f32_e32 v20, v50, v20
	v_div_scale_f32 v50, vcc, 1.0, v86, 1.0
	v_mul_f32_e32 v51, v50, v20
	v_fma_f32 v52, -v3, v51, v50
	v_fmac_f32_e32 v51, v52, v20
	v_fma_f32 v3, -v3, v51, v50
	v_div_fmas_f32 v3, v3, v20, v51
	v_div_fixup_f32 v20, v3, v86, 1.0
	v_div_scale_f32 v3, s[0:1], v89, v89, 1.0
	v_pk_mul_f32 v[50:51], v[70:71], v[20:21]
	v_pk_mul_f32 v[52:53], v[54:55], v[20:21]
	v_pk_mul_f32 v[38:39], v[38:39], v[20:21]
	v_pk_mul_f32 v[20:21], v[22:23], v[20:21]
	v_rcp_f32_e32 v22, v3
	s_nop 0
	v_fma_f32 v23, -v3, v22, 1.0
	v_fmac_f32_e32 v22, v23, v22
	v_div_scale_f32 v23, vcc, 1.0, v89, 1.0
	v_mul_f32_e32 v54, v23, v22
	v_fma_f32 v55, -v3, v54, v23
	v_fmac_f32_e32 v54, v55, v22
	v_fma_f32 v3, -v3, v54, v23
	v_div_fmas_f32 v3, v3, v22, v54
	v_div_fixup_f32 v23, v3, v89, 1.0
	v_div_scale_f32 v3, s[0:1], v88, v88, 1.0
	v_rcp_f32_e32 v22, v3
	s_nop 0
	v_fma_f32 v54, -v3, v22, 1.0
	v_fmac_f32_e32 v22, v54, v22
	v_div_scale_f32 v54, vcc, 1.0, v88, 1.0
	v_mul_f32_e32 v55, v54, v22
	v_fma_f32 v64, -v3, v55, v54
	v_fmac_f32_e32 v55, v64, v22
	v_fma_f32 v3, -v3, v55, v54
	v_div_fmas_f32 v3, v3, v22, v55
	v_div_fixup_f32 v22, v3, v88, 1.0
	v_div_scale_f32 v3, s[0:1], v91, v91, 1.0
	v_pk_mul_f32 v[54:55], v[72:73], v[22:23]
	v_pk_mul_f32 v[56:57], v[56:57], v[22:23]
	v_pk_mul_f32 v[40:41], v[40:41], v[22:23]
	v_pk_mul_f32 v[22:23], v[24:25], v[22:23]
	v_rcp_f32_e32 v24, v3
	s_nop 0
	v_fma_f32 v25, -v3, v24, 1.0
	v_fmac_f32_e32 v24, v25, v24
	v_div_scale_f32 v25, vcc, 1.0, v91, 1.0
	v_mul_f32_e32 v64, v25, v24
	v_fma_f32 v65, -v3, v64, v25
	v_fmac_f32_e32 v64, v65, v24
	v_fma_f32 v3, -v3, v64, v25
	v_div_fmas_f32 v3, v3, v24, v64
	v_div_fixup_f32 v25, v3, v91, 1.0
	v_div_scale_f32 v3, s[0:1], v90, v90, 1.0
	v_rcp_f32_e32 v24, v3
	s_nop 0
	v_fma_f32 v64, -v3, v24, 1.0
	v_fmac_f32_e32 v24, v64, v24
	v_div_scale_f32 v64, vcc, 1.0, v90, 1.0
	v_mul_f32_e32 v65, v64, v24
	v_fma_f32 v66, -v3, v65, v64
	v_fmac_f32_e32 v65, v66, v24
	v_fma_f32 v3, -v3, v65, v64
	v_div_fmas_f32 v3, v3, v24, v65
	v_div_fixup_f32 v24, v3, v90, 1.0
	v_div_scale_f32 v3, s[0:1], v93, v93, 1.0
	v_pk_mul_f32 v[64:65], v[74:75], v[24:25]
	v_pk_mul_f32 v[58:59], v[58:59], v[24:25]
; __device__ __forceinline__ unsigned cvtpk(float lo, float hi) { f32x2_t v = {lo, hi}; bf16x2_t b = __builtin_convertvector(v, bf16x2_t); return __builtin_bit_cast(unsigned, b); }
; __device__ __forceinline__ void diff_unit(const Params& p, LAS unsigned char* lds, int b, int h, int qb, float lam) {
;     ...
;     for (int mp = 0; mp < 2; ++mp) {
;         const bf16_t* Kg0 = (const bf16_t*)(p.ws + WS_KD) + ((size_t)(2 * h + mp) * MT + rowbase) * 64;
;         tile_dma<64>(Kg0, Vg0, lds + A_KOFF, lds + A_VOFF, wid, lane);
;         const bf16_t* qp = QK + (rowbase + q0 + c) * 4096 + h * 128 + 64 * mp + hh * 8;
;         bf16x8 qf[4];
; #pragma unroll
;         for (int ks = 0; ks < 4; ++ks) qf[ks] = *(const bf16x8*)(qp + 16 * ks);
; #pragma unroll
;         for (int db = 0; db < 4; ++db) O[db] = (f32x16){};
;         f32x16 L = (f32x16){};
;         f32x16 negm = (f32x16){};
;         float m = 0.f;
;         asm volatile("s_waitcnt vmcnt(0)" ::: "memory");
;         __syncthreads();
;     ...
;         for (int r = 0; r < 16; ++r) { const float a = (mp == 0 ? 1.0f : lam) / L[r];
; #pragma unroll
;             for (int db = 0; db < 4; ++db) O[db][r] *= a; }
;         if (mp == 0) {
; #pragma unroll
;             for (int db = 0; db < 4; ++db)
; #pragma unroll
;                 for (int j = 0; j < 8; ++j) park[(db * 8 + j) * 64] = cvtpk(O[db][2 * j], O[db][2 * j + 1]);
	v_pk_mul_f32 v[42:43], v[42:43], v[24:25]
	v_pk_mul_f32 v[24:25], v[26:27], v[24:25]
	v_rcp_f32_e32 v26, v3
	s_nop 0
	v_fma_f32 v27, -v3, v26, 1.0
	v_fmac_f32_e32 v26, v27, v26
	v_div_scale_f32 v27, vcc, 1.0, v93, 1.0
	v_mul_f32_e32 v66, v27, v26
	v_fma_f32 v67, -v3, v66, v27
	v_fmac_f32_e32 v66, v67, v26
	v_fma_f32 v3, -v3, v66, v27
	v_div_fmas_f32 v3, v3, v26, v66
	v_div_fixup_f32 v27, v3, v93, 1.0
	v_div_scale_f32 v3, s[0:1], v92, v92, 1.0
	v_rcp_f32_e32 v26, v3
	s_nop 0
	v_fma_f32 v66, -v3, v26, 1.0
	v_fmac_f32_e32 v26, v66, v26
	v_div_scale_f32 v66, vcc, 1.0, v92, 1.0
	v_mul_f32_e32 v67, v66, v26
	v_fma_f32 v68, -v3, v67, v66
	v_fmac_f32_e32 v67, v68, v26
	v_fma_f32 v3, -v3, v67, v66
	v_div_fmas_f32 v3, v3, v26, v67
	v_div_fixup_f32 v26, v3, v92, 1.0
	v_div_scale_f32 v3, s[0:1], v95, v95, 1.0
	v_pk_mul_f32 v[66:67], v[76:77], v[26:27]
	v_pk_mul_f32 v[60:61], v[60:61], v[26:27]
	v_pk_mul_f32 v[44:45], v[44:45], v[26:27]
	v_pk_mul_f32 v[26:27], v[28:29], v[26:27]
	v_rcp_f32_e32 v28, v3
	s_nop 0
	v_fma_f32 v29, -v3, v28, 1.0
	v_fmac_f32_e32 v28, v29, v28
	v_div_scale_f32 v29, vcc, 1.0, v95, 1.0
	v_mul_f32_e32 v68, v29, v28
	v_fma_f32 v69, -v3, v68, v29
	v_fmac_f32_e32 v68, v69, v28
	v_fma_f32 v3, -v3, v68, v29
	v_div_fmas_f32 v3, v3, v28, v68
	v_div_fixup_f32 v29, v3, v95, 1.0
	v_div_scale_f32 v3, s[0:1], v94, v94, 1.0
	v_rcp_f32_e32 v28, v3
	s_movk_i32 s0, 0x1000
	v_fma_f32 v68, -v3, v28, 1.0
	v_fmac_f32_e32 v28, v68, v28
	v_div_scale_f32 v68, vcc, 1.0, v94, 1.0
	v_mul_f32_e32 v69, v68, v28
	v_fma_f32 v70, -v3, v69, v68
	v_fmac_f32_e32 v69, v70, v28
	v_fma_f32 v3, -v3, v69, v68
	v_div_fmas_f32 v3, v3, v28, v69
	v_div_fixup_f32 v28, v3, v94, 1.0
	v_cvt_pk_bf16_f32 v3, v4, v5
	global_store_dword v2, v3, s[10:11]
	v_cvt_pk_bf16_f32 v3, v12, v13
	global_store_dword v2, v3, s[10:11] offset:256
	v_cvt_pk_bf16_f32 v3, v18, v19
	global_store_dword v2, v3, s[10:11] offset:512
	v_cvt_pk_bf16_f32 v3, v20, v21
	global_store_dword v2, v3, s[10:11] offset:768
	v_cvt_pk_bf16_f32 v3, v22, v23
	global_store_dword v2, v3, s[10:11] offset:1024
	v_cvt_pk_bf16_f32 v3, v24, v25
	v_pk_mul_f32 v[68:69], v[78:79], v[28:29]
	v_pk_mul_f32 v[62:63], v[62:63], v[28:29]
	v_pk_mul_f32 v[46:47], v[46:47], v[28:29]
	v_pk_mul_f32 v[28:29], v[30:31], v[28:29]
	global_store_dword v2, v3, s[10:11] offset:1280
	v_cvt_pk_bf16_f32 v3, v26, v27
	global_store_dword v2, v3, s[10:11] offset:1536
	v_cvt_pk_bf16_f32 v3, v28, v29
	global_store_dword v2, v3, s[10:11] offset:1792
	v_cvt_pk_bf16_f32 v3, v10, v11
	global_store_dword v2, v3, s[10:11] offset:2048
	v_cvt_pk_bf16_f32 v3, v32, v33
	global_store_dword v2, v3, s[10:11] offset:2304
	v_cvt_pk_bf16_f32 v3, v36, v37
	global_store_dword v2, v3, s[10:11] offset:2560
	v_cvt_pk_bf16_f32 v3, v38, v39
	global_store_dword v2, v3, s[10:11] offset:2816
	v_cvt_pk_bf16_f32 v3, v40, v41
	global_store_dword v2, v3, s[10:11] offset:3072
	v_cvt_pk_bf16_f32 v3, v42, v43
	global_store_dword v2, v3, s[10:11] offset:3328
	v_cvt_pk_bf16_f32 v3, v44, v45
	global_store_dword v2, v3, s[10:11] offset:3584
	v_cvt_pk_bf16_f32 v3, v46, v47
	global_store_dword v2, v3, s[10:11] offset:3840
	v_add_co_u32_e32 v2, vcc, s0, v164
	v_cvt_pk_bf16_f32 v4, v8, v9
	s_nop 0
	v_addc_co_u32_e32 v3, vcc, 0, v165, vcc
	global_store_dword v[2:3], v4, off
	v_cvt_pk_bf16_f32 v4, v16, v17
	global_store_dword v[2:3], v4, off offset:256
	v_cvt_pk_bf16_f32 v4, v48, v49
	global_store_dword v[2:3], v4, off offset:512
	v_cvt_pk_bf16_f32 v4, v52, v53
	global_store_dword v[2:3], v4, off offset:768
	v_cvt_pk_bf16_f32 v4, v56, v57
	global_store_dword v[2:3], v4, off offset:1024
	v_cvt_pk_bf16_f32 v4, v58, v59
	global_store_dword v[2:3], v4, off offset:1280
	v_cvt_pk_bf16_f32 v4, v60, v61
	global_store_dword v[2:3], v4, off offset:1536
	v_cvt_pk_bf16_f32 v4, v62, v63
	global_store_dword v[2:3], v4, off offset:1792
	v_cvt_pk_bf16_f32 v4, v6, v7
	global_store_dword v[2:3], v4, off offset:2048
	v_cvt_pk_bf16_f32 v4, v14, v15
	global_store_dword v[2:3], v4, off offset:2304
	v_cvt_pk_bf16_f32 v4, v34, v35
	global_store_dword v[2:3], v4, off offset:2560
	v_cvt_pk_bf16_f32 v4, v50, v51
	s_or_b32 s0, s87, s86
	global_store_dword v[2:3], v4, off offset:2816
	v_cvt_pk_bf16_f32 v4, v54, v55
	s_lshl_b32 s0, s0, 7
	global_store_dword v[2:3], v4, off offset:3072
	v_cvt_pk_bf16_f32 v4, v64, v65
	s_bitset1_b32 s0, 22
	global_store_dword v[2:3], v4, off offset:3328
	v_cvt_pk_bf16_f32 v4, v66, v67
	s_add_u32 s0, s27, s0
	global_store_dword v[2:3], v4, off offset:3584
	v_cvt_pk_bf16_f32 v4, v68, v69
	s_addc_u32 s1, s35, 0
	global_store_dword v[2:3], v4, off offset:3840
	v_lshl_add_u64 v[2:3], v[0:1], 1, s[0:1]
	v_lshl_add_u64 v[2:3], v[2:3], 0, v[182:183]
	global_load_lds_dwordx4 v[2:3], off
	s_mov_b32 m0, s81
	v_lshl_add_u64 v[2:3], v[2:3], 0, s[42:43]
	global_load_lds_dwordx4 v[170:171], off
	s_mov_b32 m0, s82
	s_mov_b64 s[10:11], -1
	global_load_lds_dwordx4 v[172:173], off
	global_load_dwordx4 v[156:159], v[174:175], off offset:128 nt
	global_load_dwordx4 v[152:155], v[174:175], off offset:160 nt
	global_load_dwordx4 v[148:151], v[174:175], off offset:192 nt
	global_load_dwordx4 v[144:147], v[174:175], off offset:224 nt
	s_mov_b32 m0, s83
	s_waitcnt vmcnt(0)
	s_waitcnt vmcnt(0) lgkmcnt(0)
	s_barrier
; #define LAS __attribute__((address_space(3)))
; #define MFMA32(a, b, c) __builtin_amdgcn_mfma_f32_32x32x16_bf16((a), (b), (c), 0, 0, 0)
; #define SCHEDB() __builtin_amdgcn_sched_barrier(0)
; __device__ __forceinline__ void diff_unit(const Params& p, LAS unsigned char* lds, int b, int h, int qb, float lam) {
;     ...
;         for (int jt = 0; jt < NT; ++jt) {
;             const int cur = jt & 1;
;             if (jt + 1 < NT) tile_dma<64>(Kg0 + (size_t)(jt + 1) * 4096, Vg0 + (size_t)(jt + 1) * 8192, lds + A_KOFF + (cur ^ 1) * A_KBUF, lds + A_VOFF + (cur ^ 1) * A_VBUF, wid, lane);
;             if (jt <= mylast) {
;                 const LAS unsigned char* kb = lds + A_KOFF + cur * A_KBUF + c * 128;
;                 const LAS unsigned char* vb = lds + A_VOFF + cur * A_VBUF + c * 128;
;                 f32x16 s0, s1;
;                 {
;                     bf16x8 a[2][2];
;                     { const int co = (0 ^ xk) << 4; a[0][0] = *(const LAS bf16x8*)(kb + co); a[0][1] = *(const LAS bf16x8*)(kb + 4096 + co); }
; #pragma unroll
;                     for (int ks = 0; ks < 4; ++ks) {
;                         if (ks + 1 < 4) { const int co = ((2 * (ks + 1)) ^ xk) << 4; a[(ks + 1) & 1][0] = *(const LAS bf16x8*)(kb + co); a[(ks + 1) & 1][1] = *(const LAS bf16x8*)(kb + 4096 + co); }
;                         if (ks == 0) { s0 = MFMA32(a[0][0], qf[0], negm); s1 = MFMA32(a[0][1], qf[0], negm); }
;                         else { s0 = MFMA32(a[ks & 1][0], qf[ks], s0); s1 = MFMA32(a[ks & 1][1], qf[ks], s1); }
;                         SCHEDB();
;                     }
;                 }
;                 if ((q0 - (64 * jt + 63)) < 91) {
;                     const int idx0 = (q0 + c) - (64 * jt + 16 * hh) + 64;
; #pragma unroll
;                     for (int r = 0; r < 16; ++r) { s0[r] += tab[min(idx0 - r, 255)]; s1[r] += tab[min(idx0 - 32 - r, 255)]; if ((r & 3) == 3) SCHEDB(); }
;                 }
	global_load_lds_dwordx4 v[2:3], off
	s_mov_b32 m0, s84
	s_and_b64 vcc, exec, s[64:65]
	global_load_lds_dwordx4 v[176:177], off
	s_mov_b32 m0, s85
	s_nop 0
	global_load_lds_dwordx4 v[178:179], off
	s_cbranch_vccz .LBB0_300
	ds_read_b128 v[2:5], v204
	ds_read_b128 v[18:21], v204 offset:4096
	ds_read_b128 v[34:37], v211
	ds_read_b128 v[38:41], v211 offset:4096
	s_waitcnt lgkmcnt(0)
	v_mfma_f32_32x32x16_bf16 v[2:17], v[2:5], v[156:159], 0
	v_mfma_f32_32x32x16_bf16 v[18:33], v[18:21], v[156:159], 0
	v_mfma_f32_32x32x16_bf16 v[2:17], v[34:37], v[152:155], v[2:17]
	ds_read_b128 v[34:37], v210
	ds_read_b128 v[42:45], v210 offset:4096
	v_mfma_f32_32x32x16_bf16 v[18:33], v[38:41], v[152:155], v[18:33]
	s_waitcnt lgkmcnt(0)
	v_mfma_f32_32x32x16_bf16 v[2:17], v[34:37], v[148:151], v[2:17]
	ds_read_b128 v[34:37], v209
	ds_read_b128 v[38:41], v209 offset:4096
	v_mfma_f32_32x32x16_bf16 v[18:33], v[42:45], v[148:151], v[18:33]
	s_waitcnt lgkmcnt(0)
	v_mfma_f32_32x32x16_bf16 v[2:17], v[34:37], v[144:147], v[2:17]
	v_mfma_f32_32x32x16_bf16 v[18:33], v[38:41], v[144:147], v[18:33]
	s_cmpk_gt_u32 s77, 0x99
	s_cbranch_scc1 .LBB0_299
	s_add_i32 s0, 0, 0x10000
	v_min_i32_e32 v34, 0xdf, v202
	v_lshl_add_u32 v35, v34, 2, s0
	v_min_i32_e32 v34, 0xc0, v202
	v_lshl_add_u32 v37, v34, 2, s0
	v_min_i32_e32 v34, 0xe0, v202
	v_lshl_add_u32 v38, v34, 2, s0
	v_min_i32_e32 v34, 0xc1, v202
	v_lshl_add_u32 v39, v34, 2, s0
	v_min_i32_e32 v34, 0xe1, v202
	v_min_i32_e32 v0, 0xbf, v202
	v_lshl_add_u32 v40, v34, 2, s0
	v_min_i32_e32 v34, 0xc2, v202
	v_lshl_add_u32 v0, v0, 2, s0
	v_lshl_add_u32 v41, v34, 2, s0
	v_min_i32_e32 v34, 0xe2, v202
	v_lshl_add_u32 v42, v34, 2, s0
	ds_read_b32 v34, v0 offset:256
	ds_read_b32 v36, v35 offset:128
	ds_read_b32 v35, v37 offset:252
	ds_read_b32 v37, v38 offset:124
	ds_read_b32 v38, v39 offset:248
	ds_read_b32 v40, v40 offset:120
	ds_read_b32 v39, v41 offset:244
	ds_read_b32 v41, v42 offset:116
	v_min_i32_e32 v42, 0xe3, v202
	v_lshl_add_u32 v43, v42, 2, s0
	v_min_i32_e32 v42, 0xc4, v202
	v_lshl_add_u32 v45, v42, 2, s0
	v_min_i32_e32 v42, 0xe4, v202
	v_lshl_add_u32 v46, v42, 2, s0
	v_min_i32_e32 v42, 0xc5, v202
	v_lshl_add_u32 v47, v42, 2, s0
	v_min_i32_e32 v42, 0xe5, v202
	v_min_i32_e32 v0, 0xc3, v202
	v_lshl_add_u32 v48, v42, 2, s0
	v_min_i32_e32 v42, 0xc6, v202
	v_lshl_add_u32 v0, v0, 2, s0
	v_lshl_add_u32 v49, v42, 2, s0
	v_min_i32_e32 v42, 0xe6, v202
	v_lshl_add_u32 v50, v42, 2, s0
	ds_read_b32 v42, v0 offset:240
	ds_read_b32 v44, v43 offset:112
	ds_read_b32 v43, v45 offset:236
	ds_read_b32 v45, v46 offset:108
	ds_read_b32 v46, v47 offset:232
	ds_read_b32 v48, v48 offset:104
	ds_read_b32 v47, v49 offset:228
	ds_read_b32 v49, v50 offset:100
	v_min_i32_e32 v50, 0xe7, v202
	v_lshl_add_u32 v51, v50, 2, s0
	v_min_i32_e32 v50, 0xc8, v202
	v_lshl_add_u32 v53, v50, 2, s0
	v_min_i32_e32 v50, 0xe8, v202
	v_lshl_add_u32 v54, v50, 2, s0
	v_min_i32_e32 v50, 0xc9, v202
	v_lshl_add_u32 v55, v50, 2, s0
	v_min_i32_e32 v50, 0xe9, v202
	v_min_i32_e32 v0, 0xc7, v202
	v_lshl_add_u32 v56, v50, 2, s0
	v_min_i32_e32 v50, 0xca, v202
	v_lshl_add_u32 v0, v0, 2, s0
	v_lshl_add_u32 v57, v50, 2, s0
	v_min_i32_e32 v50, 0xea, v202
	v_lshl_add_u32 v58, v50, 2, s0
	ds_read_b32 v50, v0 offset:224
	ds_read_b32 v52, v51 offset:96
	ds_read_b32 v51, v53 offset:220
	ds_read_b32 v53, v54 offset:92
	ds_read_b32 v54, v55 offset:216
	ds_read_b32 v56, v56 offset:88
	ds_read_b32 v55, v57 offset:212
	ds_read_b32 v57, v58 offset:84
	v_min_i32_e32 v0, 0xcb, v202
	s_waitcnt lgkmcnt(0)
	v_pk_add_f32 v[2:3], v[2:3], v[34:35]
	v_min_i32_e32 v34, 0xee, v202
	v_lshl_add_u32 v0, v0, 2, s0
	v_min_i32_e32 v58, 0xeb, v202
	v_min_i32_e32 v59, 0xcc, v202
	v_min_i32_e32 v60, 0xec, v202
	v_min_i32_e32 v61, 0xcd, v202
	v_min_i32_e32 v62, 0xed, v202
	v_min_i32_e32 v63, 0xce, v202
	v_pk_add_f32 v[4:5], v[4:5], v[38:39]
	v_lshl_add_u32 v39, v34, 2, s0
	v_lshl_add_u32 v58, v58, 2, s0
	v_lshl_add_u32 v59, v59, 2, s0
	v_lshl_add_u32 v60, v60, 2, s0
	v_lshl_add_u32 v61, v61, 2, s0
	v_lshl_add_u32 v62, v62, 2, s0
	v_lshl_add_u32 v63, v63, 2, s0
	v_pk_add_f32 v[8:9], v[8:9], v[46:47]
	v_pk_add_f32 v[6:7], v[6:7], v[42:43]
	ds_read_b32 v34, v0 offset:208
	ds_read_b32 v38, v58 offset:80
	ds_read_b32 v42, v61 offset:200
	ds_read_b32 v43, v63 offset:196
	ds_read_b32 v35, v59 offset:204
	ds_read_b32 v47, v39 offset:68
	ds_read_b32 v46, v62 offset:72
	ds_read_b32 v39, v60 offset:76
	v_pk_add_f32 v[12:13], v[12:13], v[54:55]
	v_pk_add_f32 v[10:11], v[10:11], v[50:51]
	s_waitcnt lgkmcnt(0)
	v_pk_add_f32 v[16:17], v[16:17], v[42:43]
	v_pk_add_f32 v[14:15], v[14:15], v[34:35]
	v_pk_add_f32 v[20:21], v[20:21], v[40:41]
	v_pk_add_f32 v[18:19], v[18:19], v[36:37]
	v_pk_add_f32 v[24:25], v[24:25], v[48:49]
	v_pk_add_f32 v[22:23], v[22:23], v[44:45]
	v_pk_add_f32 v[28:29], v[28:29], v[56:57]
	v_pk_add_f32 v[26:27], v[26:27], v[52:53]
	v_pk_add_f32 v[32:33], v[32:33], v[46:47]
	v_pk_add_f32 v[30:31], v[30:31], v[38:39]
